# diff pass prologue: early vmcnt(0) dropped so accumulator zero-init overlaps the q/K/V loads (wait at first consumer)
# speedup vs baseline: 1.0158x; 1.0044x over previous
; DI int tid() { int t = __builtin_amdgcn_workitem_id_x(); asm volatile("" : "+v"(t)); return t; }
; DI f32x16 zero16() { f32x16 z; for (int i = 0; i < 16; ++i) z[i] = 0.f; return z; }
; DI f32x16 splat16(float v) { f32x16 z; for (int i = 0; i < 16; ++i) z[i] = v; return z; }
; DI void diff_pass(const bf16_t* __restrict__ qrow  , const bf16_t* __restrict__ kg, const bf16_t* __restrict__ vg,
;                   int nkt, int q0, float negM2, f32x16 (&O)[4], float& lsum, char* lds) {
;     const int t = tid(), lane = t & 63, wv = t >> 6, h = lane >> 5, l31 = lane & 31, f = (lane >> 1) & 7;
;     const int lr = t >> 3, lc = t & 7;
;     const int sc = (lc ^ ((lr >> 1) & 7)) - lc;
;     const bf16_t* kgs = kg + sc * 8;
;     const bf16_t* vgs = vg + sc * 8;
;     const int wb = wv * 1024;
;     const int qpos = q0 + l31;
;     bf16x8 qf[4];
; #pragma unroll
;     for (int ks = 0; ks < 4; ++ks) qf[ks] = *(const bf16x8*)(qrow + 16 * ks + 8 * h);
; #pragma unroll
;     for (int d = 0; d < 4; ++d) O[d] = zero16();
;     lsum = 0.f;
;     const f32x16 minit = splat16(negM2);
;     __syncthreads();
;     __builtin_amdgcn_global_load_lds((const unsigned*)kgs, (lds_ptr_t)(lds + wb), 16, 0, 0);
;     __builtin_amdgcn_global_load_lds((const unsigned*)vgs, (lds_ptr_t)(lds + 8192 + wb), 16, 0, 0);
;     __builtin_amdgcn_global_load_lds((const unsigned*)(vgs + (size_t)64 * kS), (lds_ptr_t)(lds + 16384 + wb), 16, 0, 0);
;     asm volatile("s_waitcnt vmcnt(0)" ::: "memory");
;     __syncthreads();
.LBB0_85:
	v_mov_b32_e32 v8, v162
	s_lshl_b64 s[28:29], s[28:29], 1
	v_lshrrev_b32_e32 v6, 4, v8
	v_and_b32_e32 v0, 7, v8
	v_bitop3_b32 v6, v6, 7, v8 bitop3:0x48
	v_sub_u32_e32 v0, v6, v0
	v_bfe_u32 v9, v8, 5, 1
	v_lshlrev_b32_e32 v6, 3, v0
	v_lshlrev_b32_e32 v0, 4, v8
	v_lshl_add_u64 v[4:5], v[144:145], 0, s[28:29]
	v_ashrrev_i32_e32 v7, 31, v6
	v_and_b32_e32 v187, 0xfffffc00, v0
	v_lshlrev_b32_e32 v0, 4, v9
	v_lshl_add_u64 v[2:3], v[152:153], 0, s[28:29]
	v_lshlrev_b64 v[158:159], 1, v[6:7]
	v_lshl_add_u64 v[4:5], v[4:5], 0, v[0:1]
	v_readfirstlane_b32 s30, v187
	v_add_u32_e32 v0, 0x2000, v187
	v_lshl_add_u64 v[2:3], v[2:3], 0, v[158:159]
	global_load_dwordx4 v[140:143], v[4:5], off
	global_load_dwordx4 v[136:139], v[4:5], off offset:32
	global_load_dwordx4 v[132:135], v[4:5], off offset:64
	global_load_dwordx4 v[128:131], v[4:5], off offset:96
	s_mov_b32 m0, s30
	v_readfirstlane_b32 s30, v0
	v_add_u32_e32 v0, 0x4000, v187
	v_lshl_add_u64 v[4:5], v[150:151], 0, v[158:159]
	s_barrier
	global_load_lds_dwordx4 v[2:3], off
	s_mov_b32 m0, s30
	v_readfirstlane_b32 s30, v0
	global_load_lds_dwordx4 v[4:5], off
	v_lshl_add_u64 v[2:3], v[4:5], 0, s[94:95]
	s_mov_b32 m0, s30
	v_lshrrev_b32_e32 v0, 5, v8
	global_load_lds_dwordx4 v[2:3], off
	v_bfe_u32 v3, v8, 1, 3
	v_bitop3_b32 v0, v0, v3, 1 bitop3:0x6c
	v_lshlrev_b32_e32 v189, 4, v0
	v_bitop3_b32 v0, v9, v3, 2 bitop3:0x36
	v_lshlrev_b32_e32 v190, 4, v0
	v_bitop3_b32 v0, v9, v3, 4 bitop3:0x36
	v_and_b32_e32 v2, 31, v8
	s_nop 0
	v_lshlrev_b32_e32 v191, 4, v0
	v_bitop3_b32 v0, v9, v3, 6 bitop3:0x36
	v_mov_b32_e32 v14, v1
	v_mov_b32_e32 v15, v1
	v_or_b32_e32 v184, v2, v148
	v_lshlrev_b32_e32 v188, 7, v2
	v_lshlrev_b32_e32 v185, 2, v9
	v_lshlrev_b32_e32 v192, 4, v0
	v_mov_b32_e32 v0, v1
	v_mov_b32_e32 v2, v1
	v_mov_b32_e32 v3, v1
	v_mov_b32_e32 v4, v1
	v_mov_b32_e32 v5, v1
	v_mov_b32_e32 v6, v1
	v_mov_b32_e32 v7, v1
	v_mov_b32_e32 v8, v1
	v_mov_b32_e32 v9, v1
	v_mov_b32_e32 v10, v1
	v_mov_b32_e32 v11, v1
	v_mov_b32_e32 v12, v1
	v_mov_b32_e32 v13, v1
	v_mov_b64_e32 v[46:47], v[14:15]
	v_mov_b64_e32 v[62:63], v[14:15]
	v_mov_b64_e32 v[78:79], v[14:15]
	v_mov_b64_e32 v[94:95], v[14:15]
	s_mov_b32 s54, 1
	v_lshl_add_u64 v[160:161], v[156:157], 0, s[28:29]
	s_mov_b32 s55, 0
	v_mov_b32_e32 v186, 0
	v_mov_b64_e32 v[164:165], v[154:155]
	v_mov_b64_e32 v[44:45], v[12:13]
	v_mov_b64_e32 v[42:43], v[10:11]
	v_mov_b64_e32 v[40:41], v[8:9]
	v_mov_b64_e32 v[38:39], v[6:7]
	v_mov_b64_e32 v[36:37], v[4:5]
	v_mov_b64_e32 v[34:35], v[2:3]
	v_mov_b64_e32 v[32:33], v[0:1]
	v_mov_b64_e32 v[60:61], v[12:13]
	v_mov_b64_e32 v[58:59], v[10:11]
	v_mov_b64_e32 v[56:57], v[8:9]
	v_mov_b64_e32 v[54:55], v[6:7]
	v_mov_b64_e32 v[52:53], v[4:5]
	v_mov_b64_e32 v[50:51], v[2:3]
	v_mov_b64_e32 v[48:49], v[0:1]
	v_mov_b64_e32 v[76:77], v[12:13]
	v_mov_b64_e32 v[74:75], v[10:11]
	v_mov_b64_e32 v[72:73], v[8:9]
	v_mov_b64_e32 v[70:71], v[6:7]
	v_mov_b64_e32 v[68:69], v[4:5]
	v_mov_b64_e32 v[66:67], v[2:3]
	v_mov_b64_e32 v[64:65], v[0:1]
	v_mov_b64_e32 v[92:93], v[12:13]
	v_mov_b64_e32 v[90:91], v[10:11]
	v_mov_b64_e32 v[88:89], v[8:9]
	v_mov_b64_e32 v[86:87], v[6:7]
	v_mov_b64_e32 v[84:85], v[4:5]
	v_mov_b64_e32 v[82:83], v[2:3]
	v_mov_b64_e32 v[80:81], v[0:1]
	s_waitcnt vmcnt(0) lgkmcnt(0)
	s_barrier
	s_branch .LBB0_88
